# sample-attention item: P*V accumulation reads LDS in pipelined groups of 8 keys (same f32 FMA order; was one LDS round trip per 2 keys)
# speedup vs baseline: 1.0084x; 1.0084x over previous
.LBB0_754:
	s_or_b64 exec, exec, s[10:11]
	s_bitset1_b32 s4, 14
	s_ashr_i32 s10, s16, 6
	s_mul_i32 s12, s4, 0x600
	s_mul_hi_u32 s11, s4, 0x600
	s_add_u32 s12, s26, s12
	s_addc_u32 s13, s27, s11
	v_lshl_add_u64 v[0:1], v[8:9], 1, s[12:13]
	s_mov_b32 s11, 0x6a80000
	v_add_co_u32_e32 v0, vcc, s11, v0
	v_readlane_b32 s17, v255, 53
	s_nop 0
	v_addc_co_u32_e32 v1, vcc, 0, v1, vcc
	v_lshl_add_u32 v1, v8, 2, s17
	s_add_i32 s11, s10, 1
	v_and_b32_e32 v64, 63, v8
	v_mov_b32_e32 v0, v209
	v_lshlrev_b32_e32 v0, 16, v0
	ds_write_b32 v1, v0
	v_cvt_f32_i32_e32 v0, s11
	s_mov_b32 s11, 0x42fc0000
	s_waitcnt lgkmcnt(0)
	s_barrier
	v_cmp_lt_f32_e32 vcc, s11, v0
	s_and_b64 s[12:13], vcc, exec
	s_cselect_b32 s11, 0xffffffc0, 0
	v_cndmask_b32_e32 v1, 0, v242, vcc
	s_add_i32 s12, s10, s58
	v_sub_f32_e32 v0, v1, v0
	s_ashr_i32 s13, s12, 31
	v_exp_f32_e32 v0, v0
	s_lshl_b64 s[12:13], s[12:13], 2
	s_add_u32 s12, s22, s12
	s_addc_u32 s13, s23, s13
	global_load_dword v65, v175, s[12:13]
	s_and_b32 s12, s16, 0xffffff00
	s_and_b32 s24, s16, 0xffffffc0
	v_ldexp_f32 v0, v0, s11
	s_add_i32 s11, s12, 0
	s_lshl_b32 s13, s24, 2
	s_add_i32 s13, s17, s13
	v_mul_f32_e32 v66, 0x3fb8aa3b, v0
	v_mov_b32_e32 v0, s11
	v_mad_u32_u24 v67, v64, s72, v0
	v_mov_b32_e32 v44, s13
	ds_read_b128 v[12:15], v67
	ds_read_b128 v[16:19], v67 offset:16
	ds_read_b128 v[20:23], v67 offset:32
	ds_read_b128 v[24:27], v67 offset:48
	ds_read_b128 v[28:31], v44
	ds_read_b128 v[8:11], v44 offset:16
	ds_read_b128 v[4:7], v44 offset:32
	ds_read_b128 v[0:3], v44 offset:48
	s_add_i32 s13, s11, 0x10800
	s_waitcnt lgkmcnt(3)
	v_mul_f32_e32 v13, v13, v29
	v_fmac_f32_e32 v13, v12, v28
	v_mul_f32_e32 v12, v15, v31
	v_fmac_f32_e32 v12, v14, v30
	v_add_f32_e32 v12, v13, v12
	s_waitcnt lgkmcnt(2)
	v_mul_f32_e32 v13, v17, v9
	v_mul_f32_e32 v14, v19, v11
	v_fmac_f32_e32 v13, v16, v8
	v_fmac_f32_e32 v14, v18, v10
	v_add_f32_e32 v12, 0, v12
	v_add_f32_e32 v13, v13, v14
	v_add_f32_e32 v12, v12, v13
	s_waitcnt lgkmcnt(1)
	v_mul_f32_e32 v13, v21, v5
	v_mul_f32_e32 v14, v23, v7
	v_fmac_f32_e32 v13, v20, v4
	v_fmac_f32_e32 v14, v22, v6
	v_add_f32_e32 v13, v13, v14
	v_add_f32_e32 v12, v12, v13
	s_waitcnt lgkmcnt(0)
	v_mul_f32_e32 v13, v25, v1
	v_mul_f32_e32 v14, v27, v3
	v_fmac_f32_e32 v13, v24, v0
	v_fmac_f32_e32 v14, v26, v2
	v_add_f32_e32 v13, v13, v14
	v_add_f32_e32 v16, v12, v13
	ds_read_b128 v[12:15], v67 offset:64
	ds_read_b128 v[24:27], v44 offset:64
	v_cmp_eq_u32_e32 vcc, 0, v64
	s_waitcnt lgkmcnt(0)
	v_mul_f32_e32 v13, v13, v25
	v_fmac_f32_e32 v13, v12, v24
	v_mul_f32_e32 v12, v15, v27
	v_fmac_f32_e32 v12, v14, v26
	v_add_f32_e32 v12, v13, v12
	v_add_f32_e32 v20, v16, v12
	ds_read_b128 v[12:15], v67 offset:80
	ds_read_b128 v[16:19], v44 offset:80
	s_waitcnt lgkmcnt(0)
	v_mul_f32_e32 v13, v13, v17
	v_fmac_f32_e32 v13, v12, v16
	v_mul_f32_e32 v12, v15, v19
	v_fmac_f32_e32 v12, v14, v18
	v_add_f32_e32 v12, v13, v12
	v_add_f32_e32 v32, v20, v12
	ds_read_b128 v[12:15], v67 offset:96
	ds_read_b128 v[20:23], v44 offset:96
	s_waitcnt lgkmcnt(0)
	v_mul_f32_e32 v13, v13, v21
	v_fmac_f32_e32 v13, v12, v20
	v_mul_f32_e32 v12, v15, v23
	v_fmac_f32_e32 v12, v14, v22
	v_add_f32_e32 v12, v13, v12
	v_add_f32_e32 v36, v32, v12
	ds_read_b128 v[32:35], v67 offset:112
	ds_read_b128 v[12:15], v44 offset:112
	s_waitcnt lgkmcnt(0)
	v_mul_f32_e32 v33, v33, v13
	v_fmac_f32_e32 v33, v32, v12
	v_mul_f32_e32 v32, v35, v15
	v_fmac_f32_e32 v32, v34, v14
	v_add_f32_e32 v32, v33, v32
	v_add_f32_e32 v36, v36, v32
	ds_read_b128 v[32:35], v67 offset:128
	ds_read_b128 v[48:51], v44 offset:128
	s_waitcnt lgkmcnt(0)
	v_mul_f32_e32 v33, v33, v49
	v_fmac_f32_e32 v33, v32, v48
	v_mul_f32_e32 v32, v35, v51
	v_fmac_f32_e32 v32, v34, v50
	v_add_f32_e32 v32, v33, v32
	v_add_f32_e32 v40, v36, v32
	ds_read_b128 v[36:39], v67 offset:144
	ds_read_b128 v[32:35], v44 offset:144
	s_waitcnt lgkmcnt(0)
	v_mul_f32_e32 v37, v37, v33
	v_fmac_f32_e32 v37, v36, v32
	v_mul_f32_e32 v36, v39, v35
	v_fmac_f32_e32 v36, v38, v34
	v_add_f32_e32 v36, v37, v36
	v_add_f32_e32 v40, v40, v36
	ds_read_b128 v[36:39], v67 offset:160
	ds_read_b128 v[52:55], v44 offset:160
	s_waitcnt lgkmcnt(0)
	v_mul_f32_e32 v37, v37, v53
	v_fmac_f32_e32 v37, v36, v52
	v_mul_f32_e32 v36, v39, v55
	v_fmac_f32_e32 v36, v38, v54
	v_add_f32_e32 v36, v37, v36
	v_add_f32_e32 v45, v40, v36
	ds_read_b128 v[40:43], v67 offset:176
	ds_read_b128 v[36:39], v44 offset:176
	s_waitcnt lgkmcnt(0)
	v_mul_f32_e32 v41, v41, v37
	v_fmac_f32_e32 v41, v40, v36
	v_mul_f32_e32 v40, v43, v39
	v_fmac_f32_e32 v40, v42, v38
	v_add_f32_e32 v40, v41, v40
	v_add_f32_e32 v45, v45, v40
	ds_read_b128 v[40:43], v67 offset:192
	ds_read_b128 v[56:59], v44 offset:192
	s_waitcnt lgkmcnt(0)
	v_mul_f32_e32 v41, v41, v57
	v_fmac_f32_e32 v41, v40, v56
	v_mul_f32_e32 v40, v43, v59
	v_fmac_f32_e32 v40, v42, v58
	v_add_f32_e32 v40, v41, v40
	v_add_f32_e32 v45, v45, v40
	ds_read_b128 v[60:63], v67 offset:208
	ds_read_b128 v[40:43], v44 offset:208
	s_waitcnt lgkmcnt(0)
	v_mul_f32_e32 v46, v61, v41
	v_mul_f32_e32 v47, v63, v43
	v_fmac_f32_e32 v46, v60, v40
	v_fmac_f32_e32 v47, v62, v42
	ds_read_b128 v[68:71], v67 offset:224
	ds_read_b128 v[60:63], v44 offset:224
	v_add_f32_e32 v46, v46, v47
	v_add_f32_e32 v45, v45, v46
	s_waitcnt lgkmcnt(0)
	v_mul_f32_e32 v46, v69, v61
	v_mul_f32_e32 v47, v71, v63
	v_fmac_f32_e32 v46, v68, v60
	v_fmac_f32_e32 v47, v70, v62
	v_add_f32_e32 v46, v46, v47
	v_add_f32_e32 v72, v45, v46
	ds_read_b128 v[68:71], v67 offset:240
	ds_read_b128 v[44:47], v44 offset:240
	s_waitcnt lgkmcnt(0)
	v_mul_f32_e32 v69, v69, v45
	v_fmac_f32_e32 v69, v68, v44
	v_mul_f32_e32 v68, v71, v47
	v_fmac_f32_e32 v68, v70, v46
	v_add_f32_e32 v68, v69, v68
	v_add_f32_e32 v68, v72, v68
	ds_read_b128 v[70:73], v67 offset:33792
	v_sub_u32_e32 v69, 0x80, v64
	v_cvt_f32_ubyte0_e32 v69, v69
	v_fma_f32 v68, -v66, v69, v68
	v_or_b32_e32 v69, 64, v64
	s_waitcnt lgkmcnt(0)
	v_mul_f32_e32 v71, v29, v71
	v_fmac_f32_e32 v71, v28, v70
	v_mul_f32_e32 v70, v31, v73
	v_fmac_f32_e32 v70, v30, v72
	v_add_f32_e32 v70, v71, v70
	v_add_f32_e32 v74, 0, v70
	ds_read_b128 v[70:73], v67 offset:33808
	v_sub_u32_e32 v69, 0x80, v69
	v_cvt_f32_ubyte0_e32 v69, v69
	s_waitcnt lgkmcnt(0)
	v_mul_f32_e32 v71, v9, v71
	v_fmac_f32_e32 v71, v8, v70
	v_mul_f32_e32 v70, v11, v73
	v_fmac_f32_e32 v70, v10, v72
	v_add_f32_e32 v70, v71, v70
	v_add_f32_e32 v74, v74, v70
	ds_read_b128 v[70:73], v67 offset:33824
	s_waitcnt lgkmcnt(0)
	v_mul_f32_e32 v71, v5, v71
	v_fmac_f32_e32 v71, v4, v70
	v_mul_f32_e32 v70, v7, v73
	v_fmac_f32_e32 v70, v6, v72
	v_add_f32_e32 v70, v71, v70
	v_add_f32_e32 v74, v74, v70
	ds_read_b128 v[70:73], v67 offset:33840
	s_waitcnt lgkmcnt(0)
	v_mul_f32_e32 v71, v1, v71
	v_fmac_f32_e32 v71, v0, v70
	v_mul_f32_e32 v70, v3, v73
	v_fmac_f32_e32 v70, v2, v72
	v_add_f32_e32 v70, v71, v70
	v_add_f32_e32 v74, v74, v70
	ds_read_b128 v[70:73], v67 offset:33856
	s_waitcnt lgkmcnt(0)
	v_mul_f32_e32 v71, v25, v71
	v_fmac_f32_e32 v71, v24, v70
	v_mul_f32_e32 v70, v27, v73
	v_fmac_f32_e32 v70, v26, v72
	v_add_f32_e32 v70, v71, v70
	v_add_f32_e32 v74, v74, v70
	ds_read_b128 v[70:73], v67 offset:33872
	s_waitcnt lgkmcnt(0)
	v_mul_f32_e32 v71, v17, v71
	v_fmac_f32_e32 v71, v16, v70
	v_mul_f32_e32 v70, v19, v73
	v_fmac_f32_e32 v70, v18, v72
	v_add_f32_e32 v70, v71, v70
	v_add_f32_e32 v74, v74, v70
	ds_read_b128 v[70:73], v67 offset:33888
	s_waitcnt lgkmcnt(0)
	v_mul_f32_e32 v71, v21, v71
	v_fmac_f32_e32 v71, v20, v70
	v_mul_f32_e32 v70, v23, v73
	v_fmac_f32_e32 v70, v22, v72
	v_add_f32_e32 v70, v71, v70
	v_add_f32_e32 v74, v74, v70
	ds_read_b128 v[70:73], v67 offset:33904
	s_waitcnt lgkmcnt(0)
	v_mul_f32_e32 v71, v13, v71
	v_fmac_f32_e32 v71, v12, v70
	v_mul_f32_e32 v70, v15, v73
	v_fmac_f32_e32 v70, v14, v72
	v_add_f32_e32 v70, v71, v70
	v_add_f32_e32 v74, v74, v70
	ds_read_b128 v[70:73], v67 offset:33920
	s_waitcnt lgkmcnt(0)
	v_mul_f32_e32 v71, v49, v71
	v_fmac_f32_e32 v71, v48, v70
	v_mul_f32_e32 v70, v51, v73
	v_fmac_f32_e32 v70, v50, v72
	v_add_f32_e32 v70, v71, v70
	v_add_f32_e32 v74, v74, v70
	ds_read_b128 v[70:73], v67 offset:33936
	s_waitcnt lgkmcnt(0)
	v_mul_f32_e32 v71, v33, v71
	v_fmac_f32_e32 v71, v32, v70
	v_mul_f32_e32 v70, v35, v73
	v_fmac_f32_e32 v70, v34, v72
	v_add_f32_e32 v70, v71, v70
	v_add_f32_e32 v74, v74, v70
	ds_read_b128 v[70:73], v67 offset:33952
	s_waitcnt lgkmcnt(0)
	v_mul_f32_e32 v71, v53, v71
	v_fmac_f32_e32 v71, v52, v70
	v_mul_f32_e32 v70, v55, v73
	v_fmac_f32_e32 v70, v54, v72
	v_add_f32_e32 v70, v71, v70
	v_add_f32_e32 v74, v74, v70
	ds_read_b128 v[70:73], v67 offset:33968
	s_waitcnt lgkmcnt(0)
	v_mul_f32_e32 v71, v37, v71
	v_fmac_f32_e32 v71, v36, v70
	v_mul_f32_e32 v70, v39, v73
	v_fmac_f32_e32 v70, v38, v72
	v_add_f32_e32 v70, v71, v70
	v_add_f32_e32 v74, v74, v70
	ds_read_b128 v[70:73], v67 offset:33984
	s_waitcnt lgkmcnt(0)
	v_mul_f32_e32 v71, v57, v71
	v_fmac_f32_e32 v71, v56, v70
	v_mul_f32_e32 v70, v59, v73
	v_fmac_f32_e32 v70, v58, v72
	v_add_f32_e32 v70, v71, v70
	v_add_f32_e32 v74, v74, v70
	ds_read_b128 v[70:73], v67 offset:34000
	s_waitcnt lgkmcnt(0)
	v_mul_f32_e32 v71, v41, v71
	v_fmac_f32_e32 v71, v40, v70
	v_mul_f32_e32 v70, v43, v73
	v_fmac_f32_e32 v70, v42, v72
	v_add_f32_e32 v70, v71, v70
	v_add_f32_e32 v74, v74, v70
	ds_read_b128 v[70:73], v67 offset:34016
	s_waitcnt lgkmcnt(0)
	v_mul_f32_e32 v71, v61, v71
	v_fmac_f32_e32 v71, v60, v70
	v_mul_f32_e32 v70, v63, v73
	v_fmac_f32_e32 v70, v62, v72
	v_add_f32_e32 v70, v71, v70
	v_add_f32_e32 v74, v74, v70
	ds_read_b128 v[70:73], v67 offset:34032
	s_waitcnt lgkmcnt(0)
	v_mul_f32_e32 v67, v45, v71
	v_fmac_f32_e32 v67, v44, v70
	v_mul_f32_e32 v70, v47, v73
	v_fmac_f32_e32 v70, v46, v72
	v_add_f32_e32 v67, v67, v70
	v_add_f32_e32 v67, v74, v67
	v_fma_f32 v67, -v66, v69, v67
	v_mov_b32_e32 v69, s13
	ds_read_b128 v[70:73], v69
	s_add_i32 s13, s11, 0x10810
	s_waitcnt lgkmcnt(0)
	v_mul_f32_e32 v29, v29, v71
	v_fmac_f32_e32 v29, v28, v70
	v_mul_f32_e32 v28, v31, v73
	v_fmac_f32_e32 v28, v30, v72
	v_add_f32_e32 v28, v29, v28
	v_add_f32_e32 v69, 0, v28
	v_mov_b32_e32 v28, s13
	ds_read_b128 v[28:31], v28
	s_add_i32 s13, s11, 0x10820
	s_waitcnt lgkmcnt(0)
	v_mul_f32_e32 v9, v9, v29
	v_fmac_f32_e32 v9, v8, v28
	v_mul_f32_e32 v8, v11, v31
	v_fmac_f32_e32 v8, v10, v30
	v_add_f32_e32 v8, v9, v8
	v_add_f32_e32 v28, v69, v8
	v_mov_b32_e32 v8, s13
	ds_read_b128 v[8:11], v8
	s_add_i32 s13, s11, 0x10830
	s_waitcnt lgkmcnt(0)
	v_mul_f32_e32 v5, v5, v9
	v_fmac_f32_e32 v5, v4, v8
	v_mul_f32_e32 v4, v7, v11
	v_fmac_f32_e32 v4, v6, v10
	v_add_f32_e32 v4, v5, v4
	v_add_f32_e32 v8, v28, v4
	v_mov_b32_e32 v4, s13
	ds_read_b128 v[4:7], v4
	s_add_i32 s13, s11, 0x10840
	s_waitcnt lgkmcnt(0)
	v_mul_f32_e32 v1, v1, v5
	v_fmac_f32_e32 v1, v0, v4
	v_mul_f32_e32 v0, v3, v7
	v_fmac_f32_e32 v0, v2, v6
	v_add_f32_e32 v0, v1, v0
	v_add_f32_e32 v4, v8, v0
	v_mov_b32_e32 v0, s13
	ds_read_b128 v[0:3], v0
	s_add_i32 s13, s11, 0x10850
	s_waitcnt lgkmcnt(0)
	v_mul_f32_e32 v1, v25, v1
	v_fmac_f32_e32 v1, v24, v0
	v_mul_f32_e32 v0, v27, v3
	v_fmac_f32_e32 v0, v26, v2
	v_add_f32_e32 v0, v1, v0
	v_add_f32_e32 v4, v4, v0
	v_mov_b32_e32 v0, s13
	ds_read_b128 v[0:3], v0
	s_add_i32 s13, s11, 0x10860
	s_waitcnt lgkmcnt(0)
	v_mul_f32_e32 v1, v17, v1
	v_fmac_f32_e32 v1, v16, v0
	v_mul_f32_e32 v0, v19, v3
	v_fmac_f32_e32 v0, v18, v2
	v_add_f32_e32 v0, v1, v0
	v_add_f32_e32 v4, v4, v0
	v_mov_b32_e32 v0, s13
	ds_read_b128 v[0:3], v0
	s_add_i32 s13, s11, 0x10870
	s_waitcnt lgkmcnt(0)
	v_mul_f32_e32 v1, v21, v1
	v_fmac_f32_e32 v1, v20, v0
	v_mul_f32_e32 v0, v23, v3
	v_fmac_f32_e32 v0, v22, v2
	v_add_f32_e32 v0, v1, v0
	v_add_f32_e32 v4, v4, v0
	v_mov_b32_e32 v0, s13
	ds_read_b128 v[0:3], v0
	s_add_i32 s13, s11, 0x10880
	s_waitcnt lgkmcnt(0)
	v_mul_f32_e32 v1, v13, v1
	v_fmac_f32_e32 v1, v12, v0
	v_mul_f32_e32 v0, v15, v3
	v_fmac_f32_e32 v0, v14, v2
	v_add_f32_e32 v0, v1, v0
	v_add_f32_e32 v4, v4, v0
	v_mov_b32_e32 v0, s13
	ds_read_b128 v[0:3], v0
	s_add_i32 s13, s11, 0x10890
	s_waitcnt lgkmcnt(0)
	v_mul_f32_e32 v1, v49, v1
	v_fmac_f32_e32 v1, v48, v0
	v_mul_f32_e32 v0, v51, v3
	v_fmac_f32_e32 v0, v50, v2
	v_add_f32_e32 v0, v1, v0
	v_add_f32_e32 v4, v4, v0
	v_mov_b32_e32 v0, s13
	ds_read_b128 v[0:3], v0
	s_add_i32 s13, s11, 0x108a0
	s_waitcnt lgkmcnt(0)
	v_mul_f32_e32 v1, v33, v1
	v_fmac_f32_e32 v1, v32, v0
	v_mul_f32_e32 v0, v35, v3
	v_fmac_f32_e32 v0, v34, v2
	v_add_f32_e32 v0, v1, v0
	v_add_f32_e32 v4, v4, v0
	v_mov_b32_e32 v0, s13
	ds_read_b128 v[0:3], v0
	s_add_i32 s13, s11, 0x108b0
	s_waitcnt lgkmcnt(0)
	v_mul_f32_e32 v1, v53, v1
	v_fmac_f32_e32 v1, v52, v0
	v_mul_f32_e32 v0, v55, v3
	v_fmac_f32_e32 v0, v54, v2
	v_add_f32_e32 v0, v1, v0
	v_add_f32_e32 v4, v4, v0
	v_mov_b32_e32 v0, s13
	ds_read_b128 v[0:3], v0
	s_add_i32 s13, s11, 0x108c0
	s_waitcnt lgkmcnt(0)
	v_mul_f32_e32 v1, v37, v1
	v_fmac_f32_e32 v1, v36, v0
	v_mul_f32_e32 v0, v39, v3
	v_fmac_f32_e32 v0, v38, v2
	v_add_f32_e32 v0, v1, v0
	v_add_f32_e32 v4, v4, v0
	v_mov_b32_e32 v0, s13
	ds_read_b128 v[0:3], v0
	s_add_i32 s13, s11, 0x108d0
	s_waitcnt lgkmcnt(0)
	v_mul_f32_e32 v1, v57, v1
	v_fmac_f32_e32 v1, v56, v0
	v_mul_f32_e32 v0, v59, v3
	v_fmac_f32_e32 v0, v58, v2
	v_add_f32_e32 v0, v1, v0
	v_add_f32_e32 v4, v4, v0
	v_mov_b32_e32 v0, s13
	ds_read_b128 v[0:3], v0
	s_add_i32 s13, s11, 0x108e0
	s_add_i32 s11, s11, 0x108f0
	s_waitcnt lgkmcnt(0)
	v_mul_f32_e32 v1, v41, v1
	v_fmac_f32_e32 v1, v40, v0
	v_mul_f32_e32 v0, v43, v3
	v_fmac_f32_e32 v0, v42, v2
	v_add_f32_e32 v0, v1, v0
	v_add_f32_e32 v4, v4, v0
	v_mov_b32_e32 v0, s13
	ds_read_b128 v[0:3], v0
	s_mul_i32 s13, s10, 0x210
	s_add_i32 s16, s13, 0
	s_add_i32 s16, s16, 0x21420
	s_waitcnt lgkmcnt(0)
	v_mul_f32_e32 v1, v61, v1
	v_fmac_f32_e32 v1, v60, v0
	v_mul_f32_e32 v0, v63, v3
	v_fmac_f32_e32 v0, v62, v2
	v_add_f32_e32 v0, v1, v0
	v_add_f32_e32 v4, v4, v0
	v_mov_b32_e32 v0, s11
	ds_read_b128 v[0:3], v0
	s_waitcnt lgkmcnt(0)
	v_mul_f32_e32 v1, v45, v1
	v_fmac_f32_e32 v1, v44, v0
	v_mul_f32_e32 v0, v47, v3
	v_fmac_f32_e32 v0, v46, v2
	v_add_f32_e32 v0, v1, v0
	v_add_f32_e32 v0, v4, v0
	v_and_b32_e32 v3, 64, v237
	v_fmac_f32_e32 v0, 0x80000000, v66
	v_add_u32_e32 v3, 64, v3
	v_xor_b32_e32 v4, 1, v237
	v_cndmask_b32_e32 v2, v243, v0, vcc
	s_waitcnt vmcnt(0)
	v_mul_f32_e32 v0, 0x3fb8aa3b, v65
	v_cmp_lt_i32_e64 s[22:23], v4, v3
	v_max_f32_e32 v1, v2, v0
	v_max3_f32 v1, v68, v67, v1
	v_cndmask_b32_e64 v4, v237, v4, s[22:23]
	v_lshlrev_b32_e32 v5, 2, v4
	ds_bpermute_b32 v4, v5, v1
	s_waitcnt lgkmcnt(0)
	v_max_f32_e32 v4, v4, v4
	v_max_f32_e32 v1, v1, v4
	v_xor_b32_e32 v4, 2, v237
	v_cmp_lt_i32_e64 s[22:23], v4, v3
	s_nop 1
	v_cndmask_b32_e64 v4, v237, v4, s[22:23]
	v_lshlrev_b32_e32 v6, 2, v4
	ds_bpermute_b32 v4, v6, v1
	s_waitcnt lgkmcnt(0)
	v_max_f32_e32 v4, v4, v4
	v_max_f32_e32 v1, v1, v4
	v_xor_b32_e32 v4, 4, v237
	v_cmp_lt_i32_e64 s[22:23], v4, v3
	s_nop 1
	v_cndmask_b32_e64 v4, v237, v4, s[22:23]
	v_lshlrev_b32_e32 v7, 2, v4
	ds_bpermute_b32 v4, v7, v1
	s_waitcnt lgkmcnt(0)
	v_max_f32_e32 v4, v4, v4
	v_max_f32_e32 v1, v1, v4
	v_xor_b32_e32 v4, 8, v237
	v_cmp_lt_i32_e64 s[22:23], v4, v3
	s_nop 1
	v_cndmask_b32_e64 v4, v237, v4, s[22:23]
	v_lshlrev_b32_e32 v8, 2, v4
	ds_bpermute_b32 v4, v8, v1
	s_waitcnt lgkmcnt(0)
	v_max_f32_e32 v4, v4, v4
	v_max_f32_e32 v1, v1, v4
	v_xor_b32_e32 v4, 16, v237
	v_cmp_lt_i32_e64 s[22:23], v4, v3
	s_nop 1
	v_cndmask_b32_e64 v4, v237, v4, s[22:23]
	v_lshlrev_b32_e32 v9, 2, v4
	ds_bpermute_b32 v4, v9, v1
	s_waitcnt lgkmcnt(0)
	v_max_f32_e32 v4, v4, v4
	v_max_f32_e32 v1, v1, v4
	v_xor_b32_e32 v4, 32, v237
	v_cmp_lt_i32_e64 s[22:23], v4, v3
	s_nop 1
	v_cndmask_b32_e64 v3, v237, v4, s[22:23]
	v_lshlrev_b32_e32 v3, 2, v3
	ds_bpermute_b32 v4, v3, v1
	s_waitcnt lgkmcnt(0)
	v_max_f32_e32 v4, v4, v4
	v_max_f32_e32 v1, v1, v4
	v_sub_f32_e32 v4, v68, v1
	v_exp_f32_e32 v10, v4
	v_sub_f32_e32 v11, v67, v1
	v_exp_f32_e32 v11, v11
	v_sub_f32_e32 v2, v2, v1
	v_add_f32_e32 v4, 0, v10
	v_add_f32_e32 v12, v11, v4
	v_exp_f32_e32 v4, v2
	s_nop 0
	v_add_f32_e32 v2, v4, v12
	ds_bpermute_b32 v5, v5, v2
	s_waitcnt lgkmcnt(0)
	v_add_f32_e32 v2, v2, v5
	ds_bpermute_b32 v5, v6, v2
	s_waitcnt lgkmcnt(0)
	v_add_f32_e32 v2, v2, v5
	ds_bpermute_b32 v5, v7, v2
	s_waitcnt lgkmcnt(0)
	v_add_f32_e32 v2, v2, v5
	ds_bpermute_b32 v5, v8, v2
	s_waitcnt lgkmcnt(0)
	v_add_f32_e32 v2, v2, v5
	ds_bpermute_b32 v5, v9, v2
	s_waitcnt lgkmcnt(0)
	v_add_f32_e32 v2, v2, v5
	ds_bpermute_b32 v3, v3, v2
	v_lshl_add_u32 v5, v64, 2, s16
	ds_write2st64_b32 v5, v10, v11 offset1:1
	s_and_saveexec_b64 s[10:11], vcc
	v_mov_b32_e32 v5, s16
	ds_write_b32 v5, v4 offset:512
	s_or_b64 exec, exec, s[10:11]
	s_waitcnt lgkmcnt(0)
	s_add_i32 s10, s12, 0x10a10
	v_lshlrev_b32_e32 v149, 2, v64
	v_add_u32_e32 v149, s10, v149
	v_add_u32_e32 v150, 0x400, v149
	v_add_u32_e32 v151, 0x800, v149
	v_add_u32_e32 v152, 0xc00, v149
	s_add_i32 s11, s13, 0x21420
	v_mov_b32_e32 v148, s11
	v_mov_b32_e32 v4, 0
	ds_read_b128 v[116:119], v148
	ds_read_b128 v[120:123], v148 offset:16
	ds_read2_b32 v[124:125], v149 offset1:132
	ds_read2_b32 v[126:127], v150 offset0:8 offset1:140
	ds_read2_b32 v[128:129], v151 offset0:16 offset1:148
	ds_read2_b32 v[130:131], v152 offset0:24 offset1:156
	v_add_u32_e32 v149, 0x1080, v149
	v_add_u32_e32 v150, 0x1080, v150
	v_add_u32_e32 v151, 0x1080, v151
	v_add_u32_e32 v152, 0x1080, v152
	ds_read_b128 v[132:135], v148 offset:32
	ds_read_b128 v[136:139], v148 offset:48
	ds_read2_b32 v[140:141], v149 offset1:132
	ds_read2_b32 v[142:143], v150 offset0:8 offset1:140
	ds_read2_b32 v[144:145], v151 offset0:16 offset1:148
	ds_read2_b32 v[146:147], v152 offset0:24 offset1:156
	v_add_u32_e32 v149, 0x1080, v149
	v_add_u32_e32 v150, 0x1080, v150
	v_add_u32_e32 v151, 0x1080, v151
	v_add_u32_e32 v152, 0x1080, v152
	s_waitcnt lgkmcnt(6)
	v_fmac_f32_e32 v4, v116, v124
	v_fmac_f32_e32 v4, v117, v125
	v_fmac_f32_e32 v4, v118, v126
	v_fmac_f32_e32 v4, v119, v127
	v_fmac_f32_e32 v4, v120, v128
	v_fmac_f32_e32 v4, v121, v129
	v_fmac_f32_e32 v4, v122, v130
	v_fmac_f32_e32 v4, v123, v131
	ds_read_b128 v[116:119], v148 offset:64
	ds_read_b128 v[120:123], v148 offset:80
	ds_read2_b32 v[124:125], v149 offset1:132
	ds_read2_b32 v[126:127], v150 offset0:8 offset1:140
	ds_read2_b32 v[128:129], v151 offset0:16 offset1:148
	ds_read2_b32 v[130:131], v152 offset0:24 offset1:156
	v_add_u32_e32 v149, 0x1080, v149
	v_add_u32_e32 v150, 0x1080, v150
	v_add_u32_e32 v151, 0x1080, v151
	v_add_u32_e32 v152, 0x1080, v152
	s_waitcnt lgkmcnt(6)
	v_fmac_f32_e32 v4, v132, v140
	v_fmac_f32_e32 v4, v133, v141
	v_fmac_f32_e32 v4, v134, v142
	v_fmac_f32_e32 v4, v135, v143
	v_fmac_f32_e32 v4, v136, v144
	v_fmac_f32_e32 v4, v137, v145
	v_fmac_f32_e32 v4, v138, v146
	v_fmac_f32_e32 v4, v139, v147
	ds_read_b128 v[132:135], v148 offset:96
	ds_read_b128 v[136:139], v148 offset:112
	ds_read2_b32 v[140:141], v149 offset1:132
	ds_read2_b32 v[142:143], v150 offset0:8 offset1:140
	ds_read2_b32 v[144:145], v151 offset0:16 offset1:148
	ds_read2_b32 v[146:147], v152 offset0:24 offset1:156
	v_add_u32_e32 v149, 0x1080, v149
	v_add_u32_e32 v150, 0x1080, v150
	v_add_u32_e32 v151, 0x1080, v151
	v_add_u32_e32 v152, 0x1080, v152
	s_waitcnt lgkmcnt(6)
	v_fmac_f32_e32 v4, v116, v124
	v_fmac_f32_e32 v4, v117, v125
	v_fmac_f32_e32 v4, v118, v126
	v_fmac_f32_e32 v4, v119, v127
	v_fmac_f32_e32 v4, v120, v128
	v_fmac_f32_e32 v4, v121, v129
	v_fmac_f32_e32 v4, v122, v130
	v_fmac_f32_e32 v4, v123, v131
	ds_read_b128 v[116:119], v148 offset:128
	ds_read_b128 v[120:123], v148 offset:144
	ds_read2_b32 v[124:125], v149 offset1:132
	ds_read2_b32 v[126:127], v150 offset0:8 offset1:140
	ds_read2_b32 v[128:129], v151 offset0:16 offset1:148
	ds_read2_b32 v[130:131], v152 offset0:24 offset1:156
	v_add_u32_e32 v149, 0x1080, v149
	v_add_u32_e32 v150, 0x1080, v150
	v_add_u32_e32 v151, 0x1080, v151
	v_add_u32_e32 v152, 0x1080, v152
	s_waitcnt lgkmcnt(6)
	v_fmac_f32_e32 v4, v132, v140
	v_fmac_f32_e32 v4, v133, v141
	v_fmac_f32_e32 v4, v134, v142
	v_fmac_f32_e32 v4, v135, v143
	v_fmac_f32_e32 v4, v136, v144
	v_fmac_f32_e32 v4, v137, v145
	v_fmac_f32_e32 v4, v138, v146
	v_fmac_f32_e32 v4, v139, v147
	ds_read_b128 v[132:135], v148 offset:160
	ds_read_b128 v[136:139], v148 offset:176
	ds_read2_b32 v[140:141], v149 offset1:132
	ds_read2_b32 v[142:143], v150 offset0:8 offset1:140
	ds_read2_b32 v[144:145], v151 offset0:16 offset1:148
	ds_read2_b32 v[146:147], v152 offset0:24 offset1:156
	v_add_u32_e32 v149, 0x1080, v149
	v_add_u32_e32 v150, 0x1080, v150
	v_add_u32_e32 v151, 0x1080, v151
	v_add_u32_e32 v152, 0x1080, v152
	s_waitcnt lgkmcnt(6)
	v_fmac_f32_e32 v4, v116, v124
	v_fmac_f32_e32 v4, v117, v125
	v_fmac_f32_e32 v4, v118, v126
	v_fmac_f32_e32 v4, v119, v127
	v_fmac_f32_e32 v4, v120, v128
	v_fmac_f32_e32 v4, v121, v129
	v_fmac_f32_e32 v4, v122, v130
	v_fmac_f32_e32 v4, v123, v131
	ds_read_b128 v[116:119], v148 offset:192
	ds_read_b128 v[120:123], v148 offset:208
	ds_read2_b32 v[124:125], v149 offset1:132
	ds_read2_b32 v[126:127], v150 offset0:8 offset1:140
	ds_read2_b32 v[128:129], v151 offset0:16 offset1:148
	ds_read2_b32 v[130:131], v152 offset0:24 offset1:156
	v_add_u32_e32 v149, 0x1080, v149
	v_add_u32_e32 v150, 0x1080, v150
	v_add_u32_e32 v151, 0x1080, v151
	v_add_u32_e32 v152, 0x1080, v152
	s_waitcnt lgkmcnt(6)
	v_fmac_f32_e32 v4, v132, v140
	v_fmac_f32_e32 v4, v133, v141
	v_fmac_f32_e32 v4, v134, v142
	v_fmac_f32_e32 v4, v135, v143
	v_fmac_f32_e32 v4, v136, v144
	v_fmac_f32_e32 v4, v137, v145
	v_fmac_f32_e32 v4, v138, v146
	v_fmac_f32_e32 v4, v139, v147
	ds_read_b128 v[132:135], v148 offset:224
	ds_read_b128 v[136:139], v148 offset:240
	ds_read2_b32 v[140:141], v149 offset1:132
	ds_read2_b32 v[142:143], v150 offset0:8 offset1:140
	ds_read2_b32 v[144:145], v151 offset0:16 offset1:148
	ds_read2_b32 v[146:147], v152 offset0:24 offset1:156
	v_add_u32_e32 v149, 0x1080, v149
	v_add_u32_e32 v150, 0x1080, v150
	v_add_u32_e32 v151, 0x1080, v151
	v_add_u32_e32 v152, 0x1080, v152
	s_waitcnt lgkmcnt(6)
	v_fmac_f32_e32 v4, v116, v124
	v_fmac_f32_e32 v4, v117, v125
	v_fmac_f32_e32 v4, v118, v126
	v_fmac_f32_e32 v4, v119, v127
	v_fmac_f32_e32 v4, v120, v128
	v_fmac_f32_e32 v4, v121, v129
	v_fmac_f32_e32 v4, v122, v130
	v_fmac_f32_e32 v4, v123, v131
	ds_read_b128 v[116:119], v148 offset:256
	ds_read_b128 v[120:123], v148 offset:272
	ds_read2_b32 v[124:125], v149 offset1:132
	ds_read2_b32 v[126:127], v150 offset0:8 offset1:140
	ds_read2_b32 v[128:129], v151 offset0:16 offset1:148
	ds_read2_b32 v[130:131], v152 offset0:24 offset1:156
	v_add_u32_e32 v149, 0x1080, v149
	v_add_u32_e32 v150, 0x1080, v150
	v_add_u32_e32 v151, 0x1080, v151
	v_add_u32_e32 v152, 0x1080, v152
	s_waitcnt lgkmcnt(6)
	v_fmac_f32_e32 v4, v132, v140
	v_fmac_f32_e32 v4, v133, v141
	v_fmac_f32_e32 v4, v134, v142
	v_fmac_f32_e32 v4, v135, v143
	v_fmac_f32_e32 v4, v136, v144
	v_fmac_f32_e32 v4, v137, v145
	v_fmac_f32_e32 v4, v138, v146
	v_fmac_f32_e32 v4, v139, v147
	ds_read_b128 v[132:135], v148 offset:288
	ds_read_b128 v[136:139], v148 offset:304
	ds_read2_b32 v[140:141], v149 offset1:132
	ds_read2_b32 v[142:143], v150 offset0:8 offset1:140
	ds_read2_b32 v[144:145], v151 offset0:16 offset1:148
	ds_read2_b32 v[146:147], v152 offset0:24 offset1:156
	v_add_u32_e32 v149, 0x1080, v149
	v_add_u32_e32 v150, 0x1080, v150
	v_add_u32_e32 v151, 0x1080, v151
	v_add_u32_e32 v152, 0x1080, v152
	s_waitcnt lgkmcnt(6)
	v_fmac_f32_e32 v4, v116, v124
	v_fmac_f32_e32 v4, v117, v125
	v_fmac_f32_e32 v4, v118, v126
	v_fmac_f32_e32 v4, v119, v127
	v_fmac_f32_e32 v4, v120, v128
	v_fmac_f32_e32 v4, v121, v129
	v_fmac_f32_e32 v4, v122, v130
	v_fmac_f32_e32 v4, v123, v131
	ds_read_b128 v[116:119], v148 offset:320
	ds_read_b128 v[120:123], v148 offset:336
	ds_read2_b32 v[124:125], v149 offset1:132
	ds_read2_b32 v[126:127], v150 offset0:8 offset1:140
	ds_read2_b32 v[128:129], v151 offset0:16 offset1:148
	ds_read2_b32 v[130:131], v152 offset0:24 offset1:156
	v_add_u32_e32 v149, 0x1080, v149
	v_add_u32_e32 v150, 0x1080, v150
	v_add_u32_e32 v151, 0x1080, v151
	v_add_u32_e32 v152, 0x1080, v152
	s_waitcnt lgkmcnt(6)
	v_fmac_f32_e32 v4, v132, v140
	v_fmac_f32_e32 v4, v133, v141
	v_fmac_f32_e32 v4, v134, v142
	v_fmac_f32_e32 v4, v135, v143
	v_fmac_f32_e32 v4, v136, v144
	v_fmac_f32_e32 v4, v137, v145
	v_fmac_f32_e32 v4, v138, v146
	v_fmac_f32_e32 v4, v139, v147
	ds_read_b128 v[132:135], v148 offset:352
	ds_read_b128 v[136:139], v148 offset:368
	ds_read2_b32 v[140:141], v149 offset1:132
	ds_read2_b32 v[142:143], v150 offset0:8 offset1:140
	ds_read2_b32 v[144:145], v151 offset0:16 offset1:148
	ds_read2_b32 v[146:147], v152 offset0:24 offset1:156
	v_add_u32_e32 v149, 0x1080, v149
	v_add_u32_e32 v150, 0x1080, v150
	v_add_u32_e32 v151, 0x1080, v151
	v_add_u32_e32 v152, 0x1080, v152
	s_waitcnt lgkmcnt(6)
	v_fmac_f32_e32 v4, v116, v124
	v_fmac_f32_e32 v4, v117, v125
	v_fmac_f32_e32 v4, v118, v126
	v_fmac_f32_e32 v4, v119, v127
	v_fmac_f32_e32 v4, v120, v128
	v_fmac_f32_e32 v4, v121, v129
	v_fmac_f32_e32 v4, v122, v130
	v_fmac_f32_e32 v4, v123, v131
	ds_read_b128 v[116:119], v148 offset:384
	ds_read_b128 v[120:123], v148 offset:400
	ds_read2_b32 v[124:125], v149 offset1:132
	ds_read2_b32 v[126:127], v150 offset0:8 offset1:140
	ds_read2_b32 v[128:129], v151 offset0:16 offset1:148
	ds_read2_b32 v[130:131], v152 offset0:24 offset1:156
	v_add_u32_e32 v149, 0x1080, v149
	v_add_u32_e32 v150, 0x1080, v150
	v_add_u32_e32 v151, 0x1080, v151
	v_add_u32_e32 v152, 0x1080, v152
	s_waitcnt lgkmcnt(6)
	v_fmac_f32_e32 v4, v132, v140
	v_fmac_f32_e32 v4, v133, v141
	v_fmac_f32_e32 v4, v134, v142
	v_fmac_f32_e32 v4, v135, v143
	v_fmac_f32_e32 v4, v136, v144
	v_fmac_f32_e32 v4, v137, v145
	v_fmac_f32_e32 v4, v138, v146
	v_fmac_f32_e32 v4, v139, v147
	ds_read_b128 v[132:135], v148 offset:416
	ds_read_b128 v[136:139], v148 offset:432
	ds_read2_b32 v[140:141], v149 offset1:132
	ds_read2_b32 v[142:143], v150 offset0:8 offset1:140
	ds_read2_b32 v[144:145], v151 offset0:16 offset1:148
	ds_read2_b32 v[146:147], v152 offset0:24 offset1:156
	v_add_u32_e32 v149, 0x1080, v149
	v_add_u32_e32 v150, 0x1080, v150
	v_add_u32_e32 v151, 0x1080, v151
	v_add_u32_e32 v152, 0x1080, v152
	s_waitcnt lgkmcnt(6)
	v_fmac_f32_e32 v4, v116, v124
	v_fmac_f32_e32 v4, v117, v125
	v_fmac_f32_e32 v4, v118, v126
	v_fmac_f32_e32 v4, v119, v127
	v_fmac_f32_e32 v4, v120, v128
	v_fmac_f32_e32 v4, v121, v129
	v_fmac_f32_e32 v4, v122, v130
	v_fmac_f32_e32 v4, v123, v131
	ds_read_b128 v[116:119], v148 offset:448
	ds_read_b128 v[120:123], v148 offset:464
	ds_read2_b32 v[124:125], v149 offset1:132
	ds_read2_b32 v[126:127], v150 offset0:8 offset1:140
	ds_read2_b32 v[128:129], v151 offset0:16 offset1:148
	ds_read2_b32 v[130:131], v152 offset0:24 offset1:156
	v_add_u32_e32 v149, 0x1080, v149
	v_add_u32_e32 v150, 0x1080, v150
	v_add_u32_e32 v151, 0x1080, v151
	v_add_u32_e32 v152, 0x1080, v152
	s_waitcnt lgkmcnt(6)
	v_fmac_f32_e32 v4, v132, v140
	v_fmac_f32_e32 v4, v133, v141
	v_fmac_f32_e32 v4, v134, v142
	v_fmac_f32_e32 v4, v135, v143
	v_fmac_f32_e32 v4, v136, v144
	v_fmac_f32_e32 v4, v137, v145
	v_fmac_f32_e32 v4, v138, v146
	v_fmac_f32_e32 v4, v139, v147
	ds_read_b128 v[132:135], v148 offset:480
	ds_read_b128 v[136:139], v148 offset:496
	ds_read2_b32 v[140:141], v149 offset1:132
	ds_read2_b32 v[142:143], v150 offset0:8 offset1:140
	ds_read2_b32 v[144:145], v151 offset0:16 offset1:148
	ds_read2_b32 v[146:147], v152 offset0:24 offset1:156
	v_add_u32_e32 v149, 0x1080, v149
	v_add_u32_e32 v150, 0x1080, v150
	v_add_u32_e32 v151, 0x1080, v151
	v_add_u32_e32 v152, 0x1080, v152
	s_waitcnt lgkmcnt(6)
	v_fmac_f32_e32 v4, v116, v124
	v_fmac_f32_e32 v4, v117, v125
	v_fmac_f32_e32 v4, v118, v126
	v_fmac_f32_e32 v4, v119, v127
	v_fmac_f32_e32 v4, v120, v128
	v_fmac_f32_e32 v4, v121, v129
	v_fmac_f32_e32 v4, v122, v130
	v_fmac_f32_e32 v4, v123, v131
	ds_read_b32 v153, v148 offset:512
	ds_read_b32 v154, v149
	s_waitcnt lgkmcnt(2)
	v_fmac_f32_e32 v4, v132, v140
	v_fmac_f32_e32 v4, v133, v141
	v_fmac_f32_e32 v4, v134, v142
	v_fmac_f32_e32 v4, v135, v143
	v_fmac_f32_e32 v4, v136, v144
	v_fmac_f32_e32 v4, v137, v145
	v_fmac_f32_e32 v4, v138, v146
	v_fmac_f32_e32 v4, v139, v147
	s_waitcnt lgkmcnt(0)
	v_fmac_f32_e32 v4, v153, v154
